# S5 pass-3: stagger waves 4-7 by s_sleep 16 after each round barrier
# speedup vs baseline: 1.0020x; 1.0020x over previous
; DI float bf2f(unsigned x) { return __uint_as_float(x << 16); }
; DI void s5_pass3_item(const Params& P, int bitem, unsigned char* smem) {
;     ...
;     const bf16_t* ubase = proj + (size_t)(b * TT + ch * 64) * NPROJ + C_SSM + grp * 16;
;     bf16x8 ubs[4]; unsigned short uvs[4][4];
; #pragma unroll
;     for (int sub = 0; sub < 4; ++sub) { ubs[sub] = *(const bf16x8*)(ubase + (size_t)(sub * 16 + r) * NPROJ + 8 * (q & 1));
; #pragma unroll
;         for (int j = 0; j < 4; ++j) uvs[sub][j] = ubase[(size_t)(sub * 16 + 4 * q + j) * NPROJ + r]; }
;     float xr = 0.f, xi = 0.f;
;     {
;       const f32x2_t* e = (const f32x2_t*)(ws + WS_S5END) + (size_t)((b * 64 + grp) * 32) * 64 + lane;
;       f32x2_t ev[31];
; #pragma unroll
;       for (int j = 0; j < 31; ++j) ev[j] = e[(j < ch ? j : 0) * 64];
; #pragma unroll
;       for (int j = 0; j < 31; ++j) { const float ex = j < ch ? ev[j][0] : 0.f, ey = j < ch ? ev[j][1] : 0.f;
;           const float ncr = ab[2] * xr - ab[3] * xi + ex, nci = ab[2] * xi + ab[3] * xr + ey; xr = j < ch ? ncr : xr; xi = j < ch ? nci : xi; } }
; #pragma unroll
;     for (int sub = 0; sub < 4; ++sub) {
;         s5_bu16(ubs[sub], af, xs, r, q);
;         float uv[4];
; #pragma unroll
;         for (int j = 0; j < 4; ++j) uv[j] = bf2f(uvs[sub][j]);
.Ls5n_round:
	s_waitcnt vmcnt(16)
	v_add_u32_e32 v1, s20, v81
	ds_write_b64 v1, v[152:153] offset:0
	ds_write_b64 v1, v[154:155] offset:4096
	ds_write_b64 v1, v[156:157] offset:8192
	ds_write_b64 v1, v[158:159] offset:12288
	v_mov_b32_e32 v88, v120
	v_mov_b32_e32 v89, v121
	v_mov_b32_e32 v90, v122
	v_mov_b32_e32 v91, v123
	v_mov_b32_e32 v92, v124
	v_mov_b32_e32 v93, v125
	v_mov_b32_e32 v94, v126
	v_mov_b32_e32 v95, v127
	v_mov_b32_e32 v96, v128
	v_mov_b32_e32 v97, v129
	v_mov_b32_e32 v98, v130
	v_mov_b32_e32 v99, v131
	v_mov_b32_e32 v100, v132
	v_mov_b32_e32 v101, v133
	v_mov_b32_e32 v102, v134
	v_mov_b32_e32 v103, v135
	v_lshlrev_b32_e32 v104, 16, v136
	v_lshlrev_b32_e32 v105, 16, v137
	v_lshlrev_b32_e32 v106, 16, v138
	v_lshlrev_b32_e32 v107, 16, v139
	v_lshlrev_b32_e32 v108, 16, v140
	v_lshlrev_b32_e32 v109, 16, v141
	v_lshlrev_b32_e32 v110, 16, v142
	v_lshlrev_b32_e32 v111, 16, v143
	v_lshlrev_b32_e32 v112, 16, v144
	v_lshlrev_b32_e32 v113, 16, v145
	v_lshlrev_b32_e32 v114, 16, v146
	v_lshlrev_b32_e32 v115, 16, v147
	v_lshlrev_b32_e32 v116, 16, v148
	v_lshlrev_b32_e32 v117, 16, v149
	v_lshlrev_b32_e32 v118, 16, v150
	v_lshlrev_b32_e32 v119, 16, v151
	s_waitcnt lgkmcnt(0)
	s_barrier
	s_cmp_lt_u32 s16, 4
	s_cbranch_scc1 .Ls5n_nostag
	s_sleep 16
.Ls5n_nostag:
	s_cmp_eq_u32 s19, 7
	s_cbranch_scc1 .Ls5n_nopf
	s_add_u32 s22, s22, 0xf00000
	s_addc_u32 s23, s23, 0
	s_add_u32 s24, s24, 0x100000
	s_addc_u32 s25, s25, 0
	s_add_u32 s40, s22, 0x0
	s_addc_u32 s41, s23, 0
	s_add_u32 s42, s22, 0x1e000
	s_addc_u32 s43, s23, 0
	s_add_u32 s44, s22, 0x3c000
	s_addc_u32 s45, s23, 0
	s_add_u32 s46, s22, 0x5a000
	s_addc_u32 s47, s23, 0
	global_load_dwordx4 v[120:123], v83, s[40:41]
	global_load_dwordx4 v[124:127], v83, s[42:43]
	global_load_dwordx4 v[128:131], v83, s[44:45]
	global_load_dwordx4 v[132:135], v83, s[46:47]
	global_load_ushort v136, v84, s[40:41]
	global_load_ushort v137, v85, s[40:41]
	global_load_ushort v138, v86, s[40:41]
	global_load_ushort v139, v87, s[40:41]
	global_load_ushort v140, v84, s[42:43]
	global_load_ushort v141, v85, s[42:43]
	global_load_ushort v142, v86, s[42:43]
	global_load_ushort v143, v87, s[42:43]
	global_load_ushort v144, v84, s[44:45]
	global_load_ushort v145, v85, s[44:45]
	global_load_ushort v146, v86, s[44:45]
	global_load_ushort v147, v87, s[44:45]
	global_load_ushort v148, v84, s[46:47]
	global_load_ushort v149, v85, s[46:47]
	global_load_ushort v150, v86, s[46:47]
	global_load_ushort v151, v87, s[46:47]
	global_load_dwordx2 v[152:153], v199, s[24:25] offset:-4096
	global_load_dwordx2 v[154:155], v199, s[24:25]
	global_load_dwordx2 v[156:157], v204, s[24:25] offset:-4096
	global_load_dwordx2 v[158:159], v204, s[24:25]

; DI void s5_bu16(const bf16x8 ub, const bf16x8 (&af)[8], float* buf, int r, int q) {
; #pragma unroll
;     for (int pt = 0; pt < 8; ++pt) { f32x4 d = {0.f, 0.f, 0.f, 0.f}; d = __builtin_amdgcn_mfma_f32_16x16x32_bf16(af[pt], ub, d, 0, 0, 0);
; #pragma unroll
;         for (int j = 0; j < 4; ++j) buf[(16 * pt + 4 * q + j) * 17 + r] = d[j]; }
; DI void s5_pass3_item(const Params& P, int bitem, unsigned char* smem) {
;     ...
; #pragma unroll
;         for (int tt = 0; tt < 16; ++tt) { const float bur = xs[lane * 17 + tt], bui = xs[(64 + lane) * 17 + tt];
;             const float nxr = ab[0] * xr - ab[1] * xi + bur, nxi = ab[0] * xi + ab[1] * xr + bui; xr = nxr; xi = nxi;
;             xs[lane * 17 + tt] = xr; xs[(64 + lane) * 17 + tt] = xi; }
.Ls5n_cdone:
	s_waitcnt lgkmcnt(0)
	s_mov_b64 s[28:29], s[26:27]
	v_mfma_f32_16x16x32_bf16 v[160:163], v[8:11], v[88:91], 0
	v_mfma_f32_16x16x32_bf16 v[164:167], v[12:15], v[88:91], 0
	v_mfma_f32_16x16x32_bf16 v[168:171], v[16:19], v[88:91], 0
	v_mfma_f32_16x16x32_bf16 v[172:175], v[20:23], v[88:91], 0
	v_mfma_f32_16x16x32_bf16 v[176:179], v[24:27], v[88:91], 0
	v_mfma_f32_16x16x32_bf16 v[180:183], v[28:31], v[88:91], 0
	v_mfma_f32_16x16x32_bf16 v[184:187], v[32:35], v[88:91], 0
	v_mfma_f32_16x16x32_bf16 v[188:191], v[36:39], v[88:91], 0
	s_nop 1
	ds_write_b32 v77, v160 offset:0
	ds_write_b32 v77, v161 offset:68
	ds_write_b32 v77, v162 offset:136
	ds_write_b32 v77, v163 offset:204
	ds_write_b32 v77, v164 offset:1088
	ds_write_b32 v77, v165 offset:1156
	ds_write_b32 v77, v166 offset:1224
	ds_write_b32 v77, v167 offset:1292
	ds_write_b32 v77, v168 offset:2176
	ds_write_b32 v77, v169 offset:2244
	ds_write_b32 v77, v170 offset:2312
	ds_write_b32 v77, v171 offset:2380
	ds_write_b32 v77, v172 offset:3264
	ds_write_b32 v77, v173 offset:3332
	ds_write_b32 v77, v174 offset:3400
	ds_write_b32 v77, v175 offset:3468
	ds_write_b32 v77, v176 offset:4352
	ds_write_b32 v77, v177 offset:4420
	ds_write_b32 v77, v178 offset:4488
	ds_write_b32 v77, v179 offset:4556
	ds_write_b32 v77, v180 offset:5440
	ds_write_b32 v77, v181 offset:5508
	ds_write_b32 v77, v182 offset:5576
	ds_write_b32 v77, v183 offset:5644
	ds_write_b32 v77, v184 offset:6528
	ds_write_b32 v77, v185 offset:6596
	ds_write_b32 v77, v186 offset:6664
	ds_write_b32 v77, v187 offset:6732
	ds_write_b32 v77, v188 offset:7616
	ds_write_b32 v77, v189 offset:7684
	ds_write_b32 v77, v190 offset:7752
	ds_write_b32 v77, v191 offset:7820
	ds_read2_b32 v[208:209], v78 offset0:0 offset1:1
	ds_read2_b32 v[224:225], v79 offset0:0 offset1:1
	ds_read2_b32 v[210:211], v78 offset0:2 offset1:3
	ds_read2_b32 v[226:227], v79 offset0:2 offset1:3
	ds_read2_b32 v[212:213], v78 offset0:4 offset1:5
	ds_read2_b32 v[228:229], v79 offset0:4 offset1:5
	ds_read2_b32 v[214:215], v78 offset0:6 offset1:7
	ds_read2_b32 v[230:231], v79 offset0:6 offset1:7
	ds_read2_b32 v[216:217], v78 offset0:8 offset1:9
	ds_read2_b32 v[232:233], v79 offset0:8 offset1:9
	ds_read2_b32 v[218:219], v78 offset0:10 offset1:11
	ds_read2_b32 v[234:235], v79 offset0:10 offset1:11
	ds_read2_b32 v[220:221], v78 offset0:12 offset1:13
	ds_read2_b32 v[236:237], v79 offset0:12 offset1:13
	ds_read2_b32 v[222:223], v78 offset0:14 offset1:15
	ds_read2_b32 v[238:239], v79 offset0:14 offset1:15
	s_waitcnt lgkmcnt(14)
	v_mul_f32_e32 v194, v73, v193
	v_mul_f32_e32 v195, v73, v192
	v_fma_f32 v194, v72, v192, -v194
	v_fma_f32 v195, v72, v193, v195
	v_add_f32_e32 v208, v194, v208
	v_add_f32_e32 v224, v195, v224
	v_mul_f32_e32 v194, v73, v224
	v_mul_f32_e32 v195, v73, v208
	v_fma_f32 v194, v72, v208, -v194
	v_fma_f32 v195, v72, v224, v195
	v_add_f32_e32 v209, v194, v209
	v_add_f32_e32 v225, v195, v225
	ds_write2_b32 v78, v208, v209 offset0:0 offset1:1
	ds_write2_b32 v79, v224, v225 offset0:0 offset1:1
	s_waitcnt lgkmcnt(14)
	v_mul_f32_e32 v194, v73, v225
	v_mul_f32_e32 v195, v73, v209
	v_fma_f32 v194, v72, v209, -v194
	v_fma_f32 v195, v72, v225, v195
	v_add_f32_e32 v210, v194, v210
	v_add_f32_e32 v226, v195, v226
	v_mul_f32_e32 v194, v73, v226
	v_mul_f32_e32 v195, v73, v210
	v_fma_f32 v194, v72, v210, -v194
	v_fma_f32 v195, v72, v226, v195
	v_add_f32_e32 v211, v194, v211
	v_add_f32_e32 v227, v195, v227
	ds_write2_b32 v78, v210, v211 offset0:2 offset1:3
	ds_write2_b32 v79, v226, v227 offset0:2 offset1:3
	s_waitcnt lgkmcnt(14)
	v_mul_f32_e32 v194, v73, v227
	v_mul_f32_e32 v195, v73, v211
	v_fma_f32 v194, v72, v211, -v194
	v_fma_f32 v195, v72, v227, v195
	v_add_f32_e32 v212, v194, v212
	v_add_f32_e32 v228, v195, v228
	v_mul_f32_e32 v194, v73, v228
	v_mul_f32_e32 v195, v73, v212
	v_fma_f32 v194, v72, v212, -v194
	v_fma_f32 v195, v72, v228, v195
	v_add_f32_e32 v213, v194, v213
	v_add_f32_e32 v229, v195, v229
	ds_write2_b32 v78, v212, v213 offset0:4 offset1:5
	ds_write2_b32 v79, v228, v229 offset0:4 offset1:5
	s_waitcnt lgkmcnt(14)
	v_mul_f32_e32 v194, v73, v229
	v_mul_f32_e32 v195, v73, v213
	v_fma_f32 v194, v72, v213, -v194
	v_fma_f32 v195, v72, v229, v195
	v_add_f32_e32 v214, v194, v214
	v_add_f32_e32 v230, v195, v230
	v_mul_f32_e32 v194, v73, v230
	v_mul_f32_e32 v195, v73, v214
	v_fma_f32 v194, v72, v214, -v194
	v_fma_f32 v195, v72, v230, v195
	v_add_f32_e32 v215, v194, v215
	v_add_f32_e32 v231, v195, v231
	ds_write2_b32 v78, v214, v215 offset0:6 offset1:7
	ds_write2_b32 v79, v230, v231 offset0:6 offset1:7
	s_waitcnt lgkmcnt(14)
	v_mul_f32_e32 v194, v73, v231
	v_mul_f32_e32 v195, v73, v215
	v_fma_f32 v194, v72, v215, -v194
	v_fma_f32 v195, v72, v231, v195
	v_add_f32_e32 v216, v194, v216
	v_add_f32_e32 v232, v195, v232
	v_mul_f32_e32 v194, v73, v232
	v_mul_f32_e32 v195, v73, v216
	v_fma_f32 v194, v72, v216, -v194
	v_fma_f32 v195, v72, v232, v195
	v_add_f32_e32 v217, v194, v217
	v_add_f32_e32 v233, v195, v233
	ds_write2_b32 v78, v216, v217 offset0:8 offset1:9
	ds_write2_b32 v79, v232, v233 offset0:8 offset1:9
	s_waitcnt lgkmcnt(14)
	v_mul_f32_e32 v194, v73, v233
	v_mul_f32_e32 v195, v73, v217
	v_fma_f32 v194, v72, v217, -v194
	v_fma_f32 v195, v72, v233, v195
	v_add_f32_e32 v218, v194, v218
	v_add_f32_e32 v234, v195, v234
	v_mul_f32_e32 v194, v73, v234
	v_mul_f32_e32 v195, v73, v218
	v_fma_f32 v194, v72, v218, -v194
	v_fma_f32 v195, v72, v234, v195
	v_add_f32_e32 v219, v194, v219
	v_add_f32_e32 v235, v195, v235
	ds_write2_b32 v78, v218, v219 offset0:10 offset1:11
	ds_write2_b32 v79, v234, v235 offset0:10 offset1:11
	s_waitcnt lgkmcnt(14)
; DI void s5_pass3_item(const Params& P, int bitem, unsigned char* smem) {
;     ...
; #pragma unroll
;         for (int tt = 0; tt < 16; ++tt) { const float bur = xs[lane * 17 + tt], bui = xs[(64 + lane) * 17 + tt];
;             const float nxr = ab[0] * xr - ab[1] * xi + bur, nxi = ab[0] * xi + ab[1] * xr + bui; xr = nxr; xi = nxi;
;             xs[lane * 17 + tt] = xr; xs[(64 + lane) * 17 + tt] = xi; }
;         asm volatile("s_waitcnt lgkmcnt(0)" ::: "memory");
;         f32x4 ya[4];
; #pragma unroll
;         for (int j = 0; j < 4; ++j) ya[j] = (f32x4){0.f, 0.f, 0.f, 0.f};
; #pragma unroll
;         for (int i = 0; i < 32; ++i) { const float a = xs[(4 * i + q) * 17 + r]; ya[i & 3] = __builtin_amdgcn_mfma_f32_16x16x4f32(a, cB[i], ya[i & 3], 0, 0, 0); }
;         const f32x4 y = (ya[0] + ya[1]) + (ya[2] + ya[3]);
	v_mul_f32_e32 v194, v73, v235
	v_mul_f32_e32 v195, v73, v219
	v_fma_f32 v194, v72, v219, -v194
	v_fma_f32 v195, v72, v235, v195
	v_add_f32_e32 v220, v194, v220
	v_add_f32_e32 v236, v195, v236
	v_mul_f32_e32 v194, v73, v236
	v_mul_f32_e32 v195, v73, v220
	v_fma_f32 v194, v72, v220, -v194
	v_fma_f32 v195, v72, v236, v195
	v_add_f32_e32 v221, v194, v221
	v_add_f32_e32 v237, v195, v237
	ds_write2_b32 v78, v220, v221 offset0:12 offset1:13
	ds_write2_b32 v79, v236, v237 offset0:12 offset1:13
	s_waitcnt lgkmcnt(14)
	v_mul_f32_e32 v194, v73, v237
	v_mul_f32_e32 v195, v73, v221
	v_fma_f32 v194, v72, v221, -v194
	v_fma_f32 v195, v72, v237, v195
	v_add_f32_e32 v222, v194, v222
	v_add_f32_e32 v238, v195, v238
	v_mul_f32_e32 v194, v73, v238
	v_mul_f32_e32 v195, v73, v222
	v_fma_f32 v194, v72, v222, -v194
	v_fma_f32 v195, v72, v238, v195
	v_add_f32_e32 v223, v194, v223
	v_add_f32_e32 v239, v195, v239
	ds_write2_b32 v78, v222, v223 offset0:14 offset1:15
	ds_write2_b32 v79, v238, v239 offset0:14 offset1:15
	v_mov_b32_e32 v192, v223
	v_mov_b32_e32 v193, v239
	ds_read_b32 v160, v80 offset:0
	ds_read_b32 v161, v80 offset:272
	ds_read_b32 v162, v80 offset:544
	ds_read_b32 v163, v80 offset:816
	ds_read_b32 v164, v80 offset:1088
	ds_read_b32 v165, v80 offset:1360
	ds_read_b32 v166, v80 offset:1632
	ds_read_b32 v167, v80 offset:1904
	ds_read_b32 v168, v80 offset:2176
	ds_read_b32 v169, v80 offset:2448
	ds_read_b32 v170, v80 offset:2720
	ds_read_b32 v171, v80 offset:2992
	ds_read_b32 v172, v80 offset:3264
	ds_read_b32 v173, v80 offset:3536
	ds_read_b32 v174, v80 offset:3808
	ds_read_b32 v175, v80 offset:4080
	ds_read_b32 v176, v80 offset:4352
	ds_read_b32 v177, v80 offset:4624
	ds_read_b32 v178, v80 offset:4896
	ds_read_b32 v179, v80 offset:5168
	ds_read_b32 v180, v80 offset:5440
	ds_read_b32 v181, v80 offset:5712
	ds_read_b32 v182, v80 offset:5984
	ds_read_b32 v183, v80 offset:6256
	ds_read_b32 v184, v80 offset:6528
	ds_read_b32 v185, v80 offset:6800
	ds_read_b32 v186, v80 offset:7072
	ds_read_b32 v187, v80 offset:7344
	ds_read_b32 v188, v80 offset:7616
	ds_read_b32 v189, v80 offset:7888
	ds_read_b32 v190, v80 offset:8160
	ds_read_b32 v191, v80 offset:8432
	s_waitcnt lgkmcnt(15)
	v_mfma_f32_16x16x4_f32 v[200:203], v160, v40, 0
	s_waitcnt lgkmcnt(15)
	v_mfma_f32_16x16x4_f32 v[240:243], v161, v41, 0
	s_waitcnt lgkmcnt(15)
	v_mfma_f32_16x16x4_f32 v[200:203], v162, v42, v[200:203]
	s_waitcnt lgkmcnt(15)
	v_mfma_f32_16x16x4_f32 v[240:243], v163, v43, v[240:243]
	s_waitcnt lgkmcnt(15)
	v_mfma_f32_16x16x4_f32 v[200:203], v164, v44, v[200:203]
	s_waitcnt lgkmcnt(15)
	v_mfma_f32_16x16x4_f32 v[240:243], v165, v45, v[240:243]
	s_waitcnt lgkmcnt(15)
	v_mfma_f32_16x16x4_f32 v[200:203], v166, v46, v[200:203]
	s_waitcnt lgkmcnt(15)
	v_mfma_f32_16x16x4_f32 v[240:243], v167, v47, v[240:243]
	s_waitcnt lgkmcnt(15)
	v_mfma_f32_16x16x4_f32 v[200:203], v168, v48, v[200:203]
	s_waitcnt lgkmcnt(15)
	v_mfma_f32_16x16x4_f32 v[240:243], v169, v49, v[240:243]
	s_waitcnt lgkmcnt(15)
	v_mfma_f32_16x16x4_f32 v[200:203], v170, v50, v[200:203]
	s_waitcnt lgkmcnt(15)
	v_mfma_f32_16x16x4_f32 v[240:243], v171, v51, v[240:243]
	s_waitcnt lgkmcnt(15)
	v_mfma_f32_16x16x4_f32 v[200:203], v172, v52, v[200:203]
	s_waitcnt lgkmcnt(15)
	v_mfma_f32_16x16x4_f32 v[240:243], v173, v53, v[240:243]
	s_waitcnt lgkmcnt(15)
	v_mfma_f32_16x16x4_f32 v[200:203], v174, v54, v[200:203]
	s_waitcnt lgkmcnt(15)
	v_mfma_f32_16x16x4_f32 v[240:243], v175, v55, v[240:243]
	s_waitcnt lgkmcnt(15)
	v_mfma_f32_16x16x4_f32 v[200:203], v176, v56, v[200:203]
	s_waitcnt lgkmcnt(14)
	v_mfma_f32_16x16x4_f32 v[240:243], v177, v57, v[240:243]
	s_waitcnt lgkmcnt(13)
	v_mfma_f32_16x16x4_f32 v[200:203], v178, v58, v[200:203]
	s_waitcnt lgkmcnt(12)
	v_mfma_f32_16x16x4_f32 v[240:243], v179, v59, v[240:243]
	s_waitcnt lgkmcnt(11)
	v_mfma_f32_16x16x4_f32 v[200:203], v180, v60, v[200:203]
	s_waitcnt lgkmcnt(10)
	v_mfma_f32_16x16x4_f32 v[240:243], v181, v61, v[240:243]
	s_waitcnt lgkmcnt(9)
	v_mfma_f32_16x16x4_f32 v[200:203], v182, v62, v[200:203]
	s_waitcnt lgkmcnt(8)
	v_mfma_f32_16x16x4_f32 v[240:243], v183, v63, v[240:243]
	s_waitcnt lgkmcnt(7)
	v_mfma_f32_16x16x4_f32 v[200:203], v184, v64, v[200:203]
	s_waitcnt lgkmcnt(6)
	v_mfma_f32_16x16x4_f32 v[240:243], v185, v65, v[240:243]
	s_waitcnt lgkmcnt(5)
	v_mfma_f32_16x16x4_f32 v[200:203], v186, v66, v[200:203]
	s_waitcnt lgkmcnt(4)
	v_mfma_f32_16x16x4_f32 v[240:243], v187, v67, v[240:243]
	s_waitcnt lgkmcnt(3)
	v_mfma_f32_16x16x4_f32 v[200:203], v188, v68, v[200:203]
	s_waitcnt lgkmcnt(2)
	v_mfma_f32_16x16x4_f32 v[240:243], v189, v69, v[240:243]
	s_waitcnt lgkmcnt(1)
	v_mfma_f32_16x16x4_f32 v[200:203], v190, v70, v[200:203]
	s_waitcnt lgkmcnt(0)
; DI unsigned pk2(float a, float b) { f32x2_t v = {a, b}; return __builtin_bit_cast(unsigned, __builtin_convertvector(v, bf16x2_t)); }
; DI float bf2f(unsigned x) { return __uint_as_float(x << 16); }
; DI float gelu_tanh(float v) { const float z = 0.7978845608028654f * (v + 0.044715f * v * v * v); const float th = 1.0f - 2.0f * __builtin_amdgcn_rcpf(__builtin_amdgcn_exp2f(2.8853900817779268f * z) + 1.0f); return 0.5f * v * (1.0f + th); }
; DI void s5_pass3_item(const Params& P, int bitem, unsigned char* smem) {
;     ...
;     for (int sub = 0; sub < 4; ++sub) {
;         s5_bu16(ubs[sub], af, xs, r, q);
;         float uv[4];
; #pragma unroll
;         for (int j = 0; j < 4; ++j) uv[j] = bf2f(uvs[sub][j]);
;         asm volatile("s_waitcnt lgkmcnt(0)" ::: "memory");
; #pragma unroll
;         for (int tt = 0; tt < 16; ++tt) { const float bur = xs[lane * 17 + tt], bui = xs[(64 + lane) * 17 + tt];
;             const float nxr = ab[0] * xr - ab[1] * xi + bur, nxi = ab[0] * xi + ab[1] * xr + bui; xr = nxr; xi = nxi;
;             xs[lane * 17 + tt] = xr; xs[(64 + lane) * 17 + tt] = xi; }
;         asm volatile("s_waitcnt lgkmcnt(0)" ::: "memory");
;         f32x4 ya[4];
; #pragma unroll
;         for (int j = 0; j < 4; ++j) ya[j] = (f32x4){0.f, 0.f, 0.f, 0.f};
; #pragma unroll
;         for (int i = 0; i < 32; ++i) { const float a = xs[(4 * i + q) * 17 + r]; ya[i & 3] = __builtin_amdgcn_mfma_f32_16x16x4f32(a, cB[i], ya[i & 3], 0, 0, 0); }
;         const f32x4 y = (ya[0] + ya[1]) + (ya[2] + ya[3]);
; #pragma unroll
;         for (int j = 0; j < 4; ++j) { const int tl = sub * 16 + 4 * q + j; const float v = y[j] + dsk * uv[j];
;             HG[(size_t)(b * TT + ch * 64 + tl) * 1024 + grp * 16 + r] = (bf16_t)(pk2(gelu_tanh(v), 0.f) & 0xffffu); }
	v_mfma_f32_16x16x4_f32 v[240:243], v191, v71, v[240:243]
	s_nop 9
	v_add_f32_e32 v1, v200, v240
	v_add_f32_e32 v2, v201, v241
	v_add_f32_e32 v3, v202, v242
	v_add_f32_e32 v4, v203, v243
	v_fmac_f32_e32 v1, v76, v104
	v_fmac_f32_e32 v2, v76, v105
	v_fmac_f32_e32 v3, v76, v106
	v_fmac_f32_e32 v4, v76, v107
	v_mul_f32_e32 v5, 0x3d372713, v1
	v_mul_f32_e32 v6, 0x3d372713, v2
	v_mul_f32_e32 v7, 0x3d372713, v3
	v_mul_f32_e32 v246, 0x3d372713, v4
	v_mul_f32_e32 v5, v1, v5
	v_mul_f32_e32 v6, v2, v6
	v_mul_f32_e32 v7, v3, v7
	v_mul_f32_e32 v246, v4, v246
	v_mul_f32_e32 v194, 0.5, v1
	v_mul_f32_e32 v195, 0.5, v2
	v_mul_f32_e32 v196, 0.5, v3
	v_mul_f32_e32 v197, 0.5, v4
	v_fma_f32 v1, v1, v5, v1
	v_fma_f32 v2, v2, v6, v2
	v_fma_f32 v3, v3, v7, v3
	v_fma_f32 v4, v4, v246, v4
	v_mul_f32_e32 v1, 0x3f4c422a, v1
	v_mul_f32_e32 v2, 0x3f4c422a, v2
	v_mul_f32_e32 v3, 0x3f4c422a, v3
	v_mul_f32_e32 v4, 0x3f4c422a, v4
	v_mul_f32_e32 v1, 0x4038aa3b, v1
	v_mul_f32_e32 v2, 0x4038aa3b, v2
	v_mul_f32_e32 v3, 0x4038aa3b, v3
	v_mul_f32_e32 v4, 0x4038aa3b, v4
	v_exp_f32_e32 v1, v1
	v_exp_f32_e32 v2, v2
	v_exp_f32_e32 v3, v3
	v_exp_f32_e32 v4, v4
	v_add_f32_e32 v1, 1.0, v1
	v_add_f32_e32 v2, 1.0, v2
	v_add_f32_e32 v3, 1.0, v3
	v_add_f32_e32 v4, 1.0, v4
	v_rcp_f32_e32 v1, v1
	v_rcp_f32_e32 v2, v2
	v_rcp_f32_e32 v3, v3
	v_rcp_f32_e32 v4, v4
	v_fma_f32 v1, v1, -2.0, 1.0
	v_fma_f32 v2, v2, -2.0, 1.0
	v_fma_f32 v3, v3, -2.0, 1.0
	v_fma_f32 v4, v4, -2.0, 1.0
	v_add_f32_e32 v1, 1.0, v1
	v_add_f32_e32 v2, 1.0, v2
	v_add_f32_e32 v3, 1.0, v3
	v_add_f32_e32 v4, 1.0, v4
	v_mul_f32_e32 v1, v194, v1
	v_mul_f32_e32 v2, v195, v2
	v_mul_f32_e32 v3, v196, v3
	v_mul_f32_e32 v4, v197, v4
	v_cvt_pk_bf16_f32 v1, v1, v1
	v_cvt_pk_bf16_f32 v2, v2, v2
	v_cvt_pk_bf16_f32 v3, v3, v3
	v_cvt_pk_bf16_f32 v4, v4, v4
	global_store_short v198, v1, s[28:29] offset:-4096
	global_store_short v198, v2, s[28:29] offset:-2048
	global_store_short v198, v3, s[28:29] offset:0
	global_store_short v198, v4, s[28:29] offset:2048
	s_add_u32 s28, s28, 0x8000
	s_addc_u32 s29, s29, 0
	v_mfma_f32_16x16x32_bf16 v[160:163], v[8:11], v[92:95], 0
	v_mfma_f32_16x16x32_bf16 v[164:167], v[12:15], v[92:95], 0
	v_mfma_f32_16x16x32_bf16 v[168:171], v[16:19], v[92:95], 0
	v_mfma_f32_16x16x32_bf16 v[172:175], v[20:23], v[92:95], 0
	v_mfma_f32_16x16x32_bf16 v[176:179], v[24:27], v[92:95], 0
	v_mfma_f32_16x16x32_bf16 v[180:183], v[28:31], v[92:95], 0
	v_mfma_f32_16x16x32_bf16 v[184:187], v[32:35], v[92:95], 0
	v_mfma_f32_16x16x32_bf16 v[188:191], v[36:39], v[92:95], 0
	s_nop 1
	ds_write_b32 v77, v160 offset:0
	ds_write_b32 v77, v161 offset:68
	ds_write_b32 v77, v162 offset:136
	ds_write_b32 v77, v163 offset:204
	ds_write_b32 v77, v164 offset:1088
	ds_write_b32 v77, v165 offset:1156
	ds_write_b32 v77, v166 offset:1224
	ds_write_b32 v77, v167 offset:1292
	ds_write_b32 v77, v168 offset:2176
	ds_write_b32 v77, v169 offset:2244
	ds_write_b32 v77, v170 offset:2312
	ds_write_b32 v77, v171 offset:2380
	ds_write_b32 v77, v172 offset:3264
	ds_write_b32 v77, v173 offset:3332
	ds_write_b32 v77, v174 offset:3400
	ds_write_b32 v77, v175 offset:3468
	ds_write_b32 v77, v176 offset:4352
	ds_write_b32 v77, v177 offset:4420
	ds_write_b32 v77, v178 offset:4488
	ds_write_b32 v77, v179 offset:4556
	ds_write_b32 v77, v180 offset:5440
	ds_write_b32 v77, v181 offset:5508
	ds_write_b32 v77, v182 offset:5576
	ds_write_b32 v77, v183 offset:5644
	ds_write_b32 v77, v184 offset:6528
	ds_write_b32 v77, v185 offset:6596
	ds_write_b32 v77, v186 offset:6664
	ds_write_b32 v77, v187 offset:6732
	ds_write_b32 v77, v188 offset:7616
	ds_write_b32 v77, v189 offset:7684
	ds_write_b32 v77, v190 offset:7752
	ds_write_b32 v77, v191 offset:7820
	ds_read2_b32 v[208:209], v78 offset0:0 offset1:1
	ds_read2_b32 v[224:225], v79 offset0:0 offset1:1
	ds_read2_b32 v[210:211], v78 offset0:2 offset1:3
	ds_read2_b32 v[226:227], v79 offset0:2 offset1:3
	ds_read2_b32 v[212:213], v78 offset0:4 offset1:5
	ds_read2_b32 v[228:229], v79 offset0:4 offset1:5
	ds_read2_b32 v[214:215], v78 offset0:6 offset1:7
	ds_read2_b32 v[230:231], v79 offset0:6 offset1:7
	ds_read2_b32 v[216:217], v78 offset0:8 offset1:9
	ds_read2_b32 v[232:233], v79 offset0:8 offset1:9
	ds_read2_b32 v[218:219], v78 offset0:10 offset1:11
	ds_read2_b32 v[234:235], v79 offset0:10 offset1:11
	ds_read2_b32 v[220:221], v78 offset0:12 offset1:13
	ds_read2_b32 v[236:237], v79 offset0:12 offset1:13
	ds_read2_b32 v[222:223], v78 offset0:14 offset1:15
	ds_read2_b32 v[238:239], v79 offset0:14 offset1:15
	s_waitcnt lgkmcnt(14)
	v_mul_f32_e32 v194, v73, v193
	v_mul_f32_e32 v195, v73, v192
	v_fma_f32 v194, v72, v192, -v194
	v_fma_f32 v195, v72, v193, v195
	v_add_f32_e32 v208, v194, v208
	v_add_f32_e32 v224, v195, v224
	v_mul_f32_e32 v194, v73, v224
	v_mul_f32_e32 v195, v73, v208
	v_fma_f32 v194, v72, v208, -v194
	v_fma_f32 v195, v72, v224, v195
	v_add_f32_e32 v209, v194, v209
	v_add_f32_e32 v225, v195, v225
	ds_write2_b32 v78, v208, v209 offset0:0 offset1:1
	ds_write2_b32 v79, v224, v225 offset0:0 offset1:1
	s_waitcnt lgkmcnt(14)
	v_mul_f32_e32 v194, v73, v225
	v_mul_f32_e32 v195, v73, v209
	v_fma_f32 v194, v72, v209, -v194
	v_fma_f32 v195, v72, v225, v195
	v_add_f32_e32 v210, v194, v210
	v_add_f32_e32 v226, v195, v226
	v_mul_f32_e32 v194, v73, v226
	v_mul_f32_e32 v195, v73, v210
	v_fma_f32 v194, v72, v210, -v194
	v_fma_f32 v195, v72, v226, v195
	v_add_f32_e32 v211, v194, v211
	v_add_f32_e32 v227, v195, v227
	ds_write2_b32 v78, v210, v211 offset0:2 offset1:3
	ds_write2_b32 v79, v226, v227 offset0:2 offset1:3
	s_waitcnt lgkmcnt(14)
; DI void s5_pass3_item(const Params& P, int bitem, unsigned char* smem) {
;     ...
; #pragma unroll
;         for (int tt = 0; tt < 16; ++tt) { const float bur = xs[lane * 17 + tt], bui = xs[(64 + lane) * 17 + tt];
;             const float nxr = ab[0] * xr - ab[1] * xi + bur, nxi = ab[0] * xi + ab[1] * xr + bui; xr = nxr; xi = nxi;
;             xs[lane * 17 + tt] = xr; xs[(64 + lane) * 17 + tt] = xi; }
;         asm volatile("s_waitcnt lgkmcnt(0)" ::: "memory");
;         f32x4 ya[4];
; #pragma unroll
;         for (int j = 0; j < 4; ++j) ya[j] = (f32x4){0.f, 0.f, 0.f, 0.f};
; #pragma unroll
;         for (int i = 0; i < 32; ++i) { const float a = xs[(4 * i + q) * 17 + r]; ya[i & 3] = __builtin_amdgcn_mfma_f32_16x16x4f32(a, cB[i], ya[i & 3], 0, 0, 0); }
;         const f32x4 y = (ya[0] + ya[1]) + (ya[2] + ya[3]);
	v_mul_f32_e32 v194, v73, v227
	v_mul_f32_e32 v195, v73, v211
	v_fma_f32 v194, v72, v211, -v194
	v_fma_f32 v195, v72, v227, v195
	v_add_f32_e32 v212, v194, v212
	v_add_f32_e32 v228, v195, v228
	v_mul_f32_e32 v194, v73, v228
	v_mul_f32_e32 v195, v73, v212
	v_fma_f32 v194, v72, v212, -v194
	v_fma_f32 v195, v72, v228, v195
	v_add_f32_e32 v213, v194, v213
	v_add_f32_e32 v229, v195, v229
	ds_write2_b32 v78, v212, v213 offset0:4 offset1:5
	ds_write2_b32 v79, v228, v229 offset0:4 offset1:5
	s_waitcnt lgkmcnt(14)
	v_mul_f32_e32 v194, v73, v229
	v_mul_f32_e32 v195, v73, v213
	v_fma_f32 v194, v72, v213, -v194
	v_fma_f32 v195, v72, v229, v195
	v_add_f32_e32 v214, v194, v214
	v_add_f32_e32 v230, v195, v230
	v_mul_f32_e32 v194, v73, v230
	v_mul_f32_e32 v195, v73, v214
	v_fma_f32 v194, v72, v214, -v194
	v_fma_f32 v195, v72, v230, v195
	v_add_f32_e32 v215, v194, v215
	v_add_f32_e32 v231, v195, v231
	ds_write2_b32 v78, v214, v215 offset0:6 offset1:7
	ds_write2_b32 v79, v230, v231 offset0:6 offset1:7
	s_waitcnt lgkmcnt(14)
	v_mul_f32_e32 v194, v73, v231
	v_mul_f32_e32 v195, v73, v215
	v_fma_f32 v194, v72, v215, -v194
	v_fma_f32 v195, v72, v231, v195
	v_add_f32_e32 v216, v194, v216
	v_add_f32_e32 v232, v195, v232
	v_mul_f32_e32 v194, v73, v232
	v_mul_f32_e32 v195, v73, v216
	v_fma_f32 v194, v72, v216, -v194
	v_fma_f32 v195, v72, v232, v195
	v_add_f32_e32 v217, v194, v217
	v_add_f32_e32 v233, v195, v233
	ds_write2_b32 v78, v216, v217 offset0:8 offset1:9
	ds_write2_b32 v79, v232, v233 offset0:8 offset1:9
	s_waitcnt lgkmcnt(14)
	v_mul_f32_e32 v194, v73, v233
	v_mul_f32_e32 v195, v73, v217
	v_fma_f32 v194, v72, v217, -v194
	v_fma_f32 v195, v72, v233, v195
	v_add_f32_e32 v218, v194, v218
	v_add_f32_e32 v234, v195, v234
	v_mul_f32_e32 v194, v73, v234
	v_mul_f32_e32 v195, v73, v218
	v_fma_f32 v194, v72, v218, -v194
	v_fma_f32 v195, v72, v234, v195
	v_add_f32_e32 v219, v194, v219
	v_add_f32_e32 v235, v195, v235
	ds_write2_b32 v78, v218, v219 offset0:10 offset1:11
	ds_write2_b32 v79, v234, v235 offset0:10 offset1:11
	s_waitcnt lgkmcnt(14)
	v_mul_f32_e32 v194, v73, v235
	v_mul_f32_e32 v195, v73, v219
	v_fma_f32 v194, v72, v219, -v194
	v_fma_f32 v195, v72, v235, v195
	v_add_f32_e32 v220, v194, v220
	v_add_f32_e32 v236, v195, v236
	v_mul_f32_e32 v194, v73, v236
	v_mul_f32_e32 v195, v73, v220
	v_fma_f32 v194, v72, v220, -v194
	v_fma_f32 v195, v72, v236, v195
	v_add_f32_e32 v221, v194, v221
	v_add_f32_e32 v237, v195, v237
	ds_write2_b32 v78, v220, v221 offset0:12 offset1:13
	ds_write2_b32 v79, v236, v237 offset0:12 offset1:13
	s_waitcnt lgkmcnt(14)
	v_mul_f32_e32 v194, v73, v237
	v_mul_f32_e32 v195, v73, v221
	v_fma_f32 v194, v72, v221, -v194
	v_fma_f32 v195, v72, v237, v195
	v_add_f32_e32 v222, v194, v222
	v_add_f32_e32 v238, v195, v238
	v_mul_f32_e32 v194, v73, v238
	v_mul_f32_e32 v195, v73, v222
	v_fma_f32 v194, v72, v222, -v194
	v_fma_f32 v195, v72, v238, v195
	v_add_f32_e32 v223, v194, v223
	v_add_f32_e32 v239, v195, v239
	ds_write2_b32 v78, v222, v223 offset0:14 offset1:15
	ds_write2_b32 v79, v238, v239 offset0:14 offset1:15
	v_mov_b32_e32 v192, v223
	v_mov_b32_e32 v193, v239
	ds_read_b32 v160, v80 offset:0
	ds_read_b32 v161, v80 offset:272
	ds_read_b32 v162, v80 offset:544
	ds_read_b32 v163, v80 offset:816
	ds_read_b32 v164, v80 offset:1088
	ds_read_b32 v165, v80 offset:1360
	ds_read_b32 v166, v80 offset:1632
	ds_read_b32 v167, v80 offset:1904
	ds_read_b32 v168, v80 offset:2176
	ds_read_b32 v169, v80 offset:2448
	ds_read_b32 v170, v80 offset:2720
	ds_read_b32 v171, v80 offset:2992
	ds_read_b32 v172, v80 offset:3264
	ds_read_b32 v173, v80 offset:3536
	ds_read_b32 v174, v80 offset:3808
	ds_read_b32 v175, v80 offset:4080
	ds_read_b32 v176, v80 offset:4352
	ds_read_b32 v177, v80 offset:4624
	ds_read_b32 v178, v80 offset:4896
	ds_read_b32 v179, v80 offset:5168
	ds_read_b32 v180, v80 offset:5440
	ds_read_b32 v181, v80 offset:5712
	ds_read_b32 v182, v80 offset:5984
	ds_read_b32 v183, v80 offset:6256
	ds_read_b32 v184, v80 offset:6528
	ds_read_b32 v185, v80 offset:6800
	ds_read_b32 v186, v80 offset:7072
	ds_read_b32 v187, v80 offset:7344
	ds_read_b32 v188, v80 offset:7616
	ds_read_b32 v189, v80 offset:7888
	ds_read_b32 v190, v80 offset:8160
	ds_read_b32 v191, v80 offset:8432
	s_waitcnt lgkmcnt(15)
	v_mfma_f32_16x16x4_f32 v[200:203], v160, v40, 0
	s_waitcnt lgkmcnt(15)
	v_mfma_f32_16x16x4_f32 v[240:243], v161, v41, 0
	s_waitcnt lgkmcnt(15)
	v_mfma_f32_16x16x4_f32 v[200:203], v162, v42, v[200:203]
	s_waitcnt lgkmcnt(15)
	v_mfma_f32_16x16x4_f32 v[240:243], v163, v43, v[240:243]
	s_waitcnt lgkmcnt(15)
	v_mfma_f32_16x16x4_f32 v[200:203], v164, v44, v[200:203]
	s_waitcnt lgkmcnt(15)
	v_mfma_f32_16x16x4_f32 v[240:243], v165, v45, v[240:243]
	s_waitcnt lgkmcnt(15)
	v_mfma_f32_16x16x4_f32 v[200:203], v166, v46, v[200:203]
	s_waitcnt lgkmcnt(15)
	v_mfma_f32_16x16x4_f32 v[240:243], v167, v47, v[240:243]
	s_waitcnt lgkmcnt(15)
	v_mfma_f32_16x16x4_f32 v[200:203], v168, v48, v[200:203]
	s_waitcnt lgkmcnt(15)
	v_mfma_f32_16x16x4_f32 v[240:243], v169, v49, v[240:243]
	s_waitcnt lgkmcnt(15)
	v_mfma_f32_16x16x4_f32 v[200:203], v170, v50, v[200:203]
	s_waitcnt lgkmcnt(15)
	v_mfma_f32_16x16x4_f32 v[240:243], v171, v51, v[240:243]
	s_waitcnt lgkmcnt(15)
	v_mfma_f32_16x16x4_f32 v[200:203], v172, v52, v[200:203]
	s_waitcnt lgkmcnt(15)
	v_mfma_f32_16x16x4_f32 v[240:243], v173, v53, v[240:243]
	s_waitcnt lgkmcnt(15)
	v_mfma_f32_16x16x4_f32 v[200:203], v174, v54, v[200:203]
	s_waitcnt lgkmcnt(15)
	v_mfma_f32_16x16x4_f32 v[240:243], v175, v55, v[240:243]
	s_waitcnt lgkmcnt(15)
	v_mfma_f32_16x16x4_f32 v[200:203], v176, v56, v[200:203]
	s_waitcnt lgkmcnt(14)
; DI unsigned pk2(float a, float b) { f32x2_t v = {a, b}; return __builtin_bit_cast(unsigned, __builtin_convertvector(v, bf16x2_t)); }
; DI float bf2f(unsigned x) { return __uint_as_float(x << 16); }
; DI float gelu_tanh(float v) { const float z = 0.7978845608028654f * (v + 0.044715f * v * v * v); const float th = 1.0f - 2.0f * __builtin_amdgcn_rcpf(__builtin_amdgcn_exp2f(2.8853900817779268f * z) + 1.0f); return 0.5f * v * (1.0f + th); }
; DI void s5_pass3_item(const Params& P, int bitem, unsigned char* smem) {
;     ...
;     for (int sub = 0; sub < 4; ++sub) {
;         s5_bu16(ubs[sub], af, xs, r, q);
;         float uv[4];
; #pragma unroll
;         for (int j = 0; j < 4; ++j) uv[j] = bf2f(uvs[sub][j]);
;         asm volatile("s_waitcnt lgkmcnt(0)" ::: "memory");
; #pragma unroll
;         for (int tt = 0; tt < 16; ++tt) { const float bur = xs[lane * 17 + tt], bui = xs[(64 + lane) * 17 + tt];
;             const float nxr = ab[0] * xr - ab[1] * xi + bur, nxi = ab[0] * xi + ab[1] * xr + bui; xr = nxr; xi = nxi;
;             xs[lane * 17 + tt] = xr; xs[(64 + lane) * 17 + tt] = xi; }
;         asm volatile("s_waitcnt lgkmcnt(0)" ::: "memory");
;         f32x4 ya[4];
; #pragma unroll
;         for (int j = 0; j < 4; ++j) ya[j] = (f32x4){0.f, 0.f, 0.f, 0.f};
; #pragma unroll
;         for (int i = 0; i < 32; ++i) { const float a = xs[(4 * i + q) * 17 + r]; ya[i & 3] = __builtin_amdgcn_mfma_f32_16x16x4f32(a, cB[i], ya[i & 3], 0, 0, 0); }
;         const f32x4 y = (ya[0] + ya[1]) + (ya[2] + ya[3]);
; #pragma unroll
;         for (int j = 0; j < 4; ++j) { const int tl = sub * 16 + 4 * q + j; const float v = y[j] + dsk * uv[j];
;             HG[(size_t)(b * TT + ch * 64 + tl) * 1024 + grp * 16 + r] = (bf16_t)(pk2(gelu_tanh(v), 0.f) & 0xffffu); }
	v_mfma_f32_16x16x4_f32 v[240:243], v177, v57, v[240:243]
	s_waitcnt lgkmcnt(13)
	v_mfma_f32_16x16x4_f32 v[200:203], v178, v58, v[200:203]
	s_waitcnt lgkmcnt(12)
	v_mfma_f32_16x16x4_f32 v[240:243], v179, v59, v[240:243]
	s_waitcnt lgkmcnt(11)
	v_mfma_f32_16x16x4_f32 v[200:203], v180, v60, v[200:203]
	s_waitcnt lgkmcnt(10)
	v_mfma_f32_16x16x4_f32 v[240:243], v181, v61, v[240:243]
	s_waitcnt lgkmcnt(9)
	v_mfma_f32_16x16x4_f32 v[200:203], v182, v62, v[200:203]
	s_waitcnt lgkmcnt(8)
	v_mfma_f32_16x16x4_f32 v[240:243], v183, v63, v[240:243]
	s_waitcnt lgkmcnt(7)
	v_mfma_f32_16x16x4_f32 v[200:203], v184, v64, v[200:203]
	s_waitcnt lgkmcnt(6)
	v_mfma_f32_16x16x4_f32 v[240:243], v185, v65, v[240:243]
	s_waitcnt lgkmcnt(5)
	v_mfma_f32_16x16x4_f32 v[200:203], v186, v66, v[200:203]
	s_waitcnt lgkmcnt(4)
	v_mfma_f32_16x16x4_f32 v[240:243], v187, v67, v[240:243]
	s_waitcnt lgkmcnt(3)
	v_mfma_f32_16x16x4_f32 v[200:203], v188, v68, v[200:203]
	s_waitcnt lgkmcnt(2)
	v_mfma_f32_16x16x4_f32 v[240:243], v189, v69, v[240:243]
	s_waitcnt lgkmcnt(1)
	v_mfma_f32_16x16x4_f32 v[200:203], v190, v70, v[200:203]
	s_waitcnt lgkmcnt(0)
	v_mfma_f32_16x16x4_f32 v[240:243], v191, v71, v[240:243]
	s_nop 9
	v_add_f32_e32 v1, v200, v240
	v_add_f32_e32 v2, v201, v241
	v_add_f32_e32 v3, v202, v242
	v_add_f32_e32 v4, v203, v243
	v_fmac_f32_e32 v1, v76, v108
	v_fmac_f32_e32 v2, v76, v109
	v_fmac_f32_e32 v3, v76, v110
	v_fmac_f32_e32 v4, v76, v111
	v_mul_f32_e32 v5, 0x3d372713, v1
	v_mul_f32_e32 v6, 0x3d372713, v2
	v_mul_f32_e32 v7, 0x3d372713, v3
	v_mul_f32_e32 v246, 0x3d372713, v4
	v_mul_f32_e32 v5, v1, v5
	v_mul_f32_e32 v6, v2, v6
	v_mul_f32_e32 v7, v3, v7
	v_mul_f32_e32 v246, v4, v246
	v_mul_f32_e32 v194, 0.5, v1
	v_mul_f32_e32 v195, 0.5, v2
	v_mul_f32_e32 v196, 0.5, v3
	v_mul_f32_e32 v197, 0.5, v4
	v_fma_f32 v1, v1, v5, v1
	v_fma_f32 v2, v2, v6, v2
	v_fma_f32 v3, v3, v7, v3
	v_fma_f32 v4, v4, v246, v4
	v_mul_f32_e32 v1, 0x3f4c422a, v1
	v_mul_f32_e32 v2, 0x3f4c422a, v2
	v_mul_f32_e32 v3, 0x3f4c422a, v3
	v_mul_f32_e32 v4, 0x3f4c422a, v4
	v_mul_f32_e32 v1, 0x4038aa3b, v1
	v_mul_f32_e32 v2, 0x4038aa3b, v2
	v_mul_f32_e32 v3, 0x4038aa3b, v3
	v_mul_f32_e32 v4, 0x4038aa3b, v4
	v_exp_f32_e32 v1, v1
	v_exp_f32_e32 v2, v2
	v_exp_f32_e32 v3, v3
	v_exp_f32_e32 v4, v4
	v_add_f32_e32 v1, 1.0, v1
	v_add_f32_e32 v2, 1.0, v2
	v_add_f32_e32 v3, 1.0, v3
	v_add_f32_e32 v4, 1.0, v4
	v_rcp_f32_e32 v1, v1
	v_rcp_f32_e32 v2, v2
	v_rcp_f32_e32 v3, v3
	v_rcp_f32_e32 v4, v4
	v_fma_f32 v1, v1, -2.0, 1.0
	v_fma_f32 v2, v2, -2.0, 1.0
	v_fma_f32 v3, v3, -2.0, 1.0
	v_fma_f32 v4, v4, -2.0, 1.0
	v_add_f32_e32 v1, 1.0, v1
	v_add_f32_e32 v2, 1.0, v2
	v_add_f32_e32 v3, 1.0, v3
	v_add_f32_e32 v4, 1.0, v4
	v_mul_f32_e32 v1, v194, v1
	v_mul_f32_e32 v2, v195, v2
	v_mul_f32_e32 v3, v196, v3
	v_mul_f32_e32 v4, v197, v4
	v_cvt_pk_bf16_f32 v1, v1, v1
	v_cvt_pk_bf16_f32 v2, v2, v2
	v_cvt_pk_bf16_f32 v3, v3, v3
	v_cvt_pk_bf16_f32 v4, v4, v4
	global_store_short v198, v1, s[28:29] offset:-4096
	global_store_short v198, v2, s[28:29] offset:-2048
	global_store_short v198, v3, s[28:29] offset:0
	global_store_short v198, v4, s[28:29] offset:2048
	s_add_u32 s28, s28, 0x8000
	s_addc_u32 s29, s29, 0
	v_mfma_f32_16x16x32_bf16 v[160:163], v[8:11], v[96:99], 0
	v_mfma_f32_16x16x32_bf16 v[164:167], v[12:15], v[96:99], 0
	v_mfma_f32_16x16x32_bf16 v[168:171], v[16:19], v[96:99], 0
	v_mfma_f32_16x16x32_bf16 v[172:175], v[20:23], v[96:99], 0
	v_mfma_f32_16x16x32_bf16 v[176:179], v[24:27], v[96:99], 0
	v_mfma_f32_16x16x32_bf16 v[180:183], v[28:31], v[96:99], 0
	v_mfma_f32_16x16x32_bf16 v[184:187], v[32:35], v[96:99], 0
	v_mfma_f32_16x16x32_bf16 v[188:191], v[36:39], v[96:99], 0
	s_nop 1
	ds_write_b32 v77, v160 offset:0
	ds_write_b32 v77, v161 offset:68
	ds_write_b32 v77, v162 offset:136
	ds_write_b32 v77, v163 offset:204
	ds_write_b32 v77, v164 offset:1088
	ds_write_b32 v77, v165 offset:1156
	ds_write_b32 v77, v166 offset:1224
	ds_write_b32 v77, v167 offset:1292
	ds_write_b32 v77, v168 offset:2176
	ds_write_b32 v77, v169 offset:2244
	ds_write_b32 v77, v170 offset:2312
	ds_write_b32 v77, v171 offset:2380
	ds_write_b32 v77, v172 offset:3264
	ds_write_b32 v77, v173 offset:3332
	ds_write_b32 v77, v174 offset:3400
	ds_write_b32 v77, v175 offset:3468
	ds_write_b32 v77, v176 offset:4352
	ds_write_b32 v77, v177 offset:4420
	ds_write_b32 v77, v178 offset:4488
	ds_write_b32 v77, v179 offset:4556
	ds_write_b32 v77, v180 offset:5440
	ds_write_b32 v77, v181 offset:5508
	ds_write_b32 v77, v182 offset:5576
	ds_write_b32 v77, v183 offset:5644
	ds_write_b32 v77, v184 offset:6528
	ds_write_b32 v77, v185 offset:6596
	ds_write_b32 v77, v186 offset:6664
	ds_write_b32 v77, v187 offset:6732
	ds_write_b32 v77, v188 offset:7616
	ds_write_b32 v77, v189 offset:7684
	ds_write_b32 v77, v190 offset:7752
	ds_write_b32 v77, v191 offset:7820
	ds_read2_b32 v[208:209], v78 offset0:0 offset1:1
	ds_read2_b32 v[224:225], v79 offset0:0 offset1:1
	ds_read2_b32 v[210:211], v78 offset0:2 offset1:3
	ds_read2_b32 v[226:227], v79 offset0:2 offset1:3
	ds_read2_b32 v[212:213], v78 offset0:4 offset1:5
	ds_read2_b32 v[228:229], v79 offset0:4 offset1:5
	ds_read2_b32 v[214:215], v78 offset0:6 offset1:7
	ds_read2_b32 v[230:231], v79 offset0:6 offset1:7
	ds_read2_b32 v[216:217], v78 offset0:8 offset1:9
	ds_read2_b32 v[232:233], v79 offset0:8 offset1:9
	ds_read2_b32 v[218:219], v78 offset0:10 offset1:11
	ds_read2_b32 v[234:235], v79 offset0:10 offset1:11
	ds_read2_b32 v[220:221], v78 offset0:12 offset1:13
	ds_read2_b32 v[236:237], v79 offset0:12 offset1:13
	ds_read2_b32 v[222:223], v78 offset0:14 offset1:15
	ds_read2_b32 v[238:239], v79 offset0:14 offset1:15
	s_waitcnt lgkmcnt(14)
; DI void s5_pass3_item(const Params& P, int bitem, unsigned char* smem) {
;     ...
; #pragma unroll
;         for (int tt = 0; tt < 16; ++tt) { const float bur = xs[lane * 17 + tt], bui = xs[(64 + lane) * 17 + tt];
;             const float nxr = ab[0] * xr - ab[1] * xi + bur, nxi = ab[0] * xi + ab[1] * xr + bui; xr = nxr; xi = nxi;
;             xs[lane * 17 + tt] = xr; xs[(64 + lane) * 17 + tt] = xi; }
;         asm volatile("s_waitcnt lgkmcnt(0)" ::: "memory");
;         f32x4 ya[4];
; #pragma unroll
;         for (int j = 0; j < 4; ++j) ya[j] = (f32x4){0.f, 0.f, 0.f, 0.f};
; #pragma unroll
;         for (int i = 0; i < 32; ++i) { const float a = xs[(4 * i + q) * 17 + r]; ya[i & 3] = __builtin_amdgcn_mfma_f32_16x16x4f32(a, cB[i], ya[i & 3], 0, 0, 0); }
;         const f32x4 y = (ya[0] + ya[1]) + (ya[2] + ya[3]);
	v_mul_f32_e32 v194, v73, v193
	v_mul_f32_e32 v195, v73, v192
	v_fma_f32 v194, v72, v192, -v194
	v_fma_f32 v195, v72, v193, v195
	v_add_f32_e32 v208, v194, v208
	v_add_f32_e32 v224, v195, v224
	v_mul_f32_e32 v194, v73, v224
	v_mul_f32_e32 v195, v73, v208
	v_fma_f32 v194, v72, v208, -v194
	v_fma_f32 v195, v72, v224, v195
	v_add_f32_e32 v209, v194, v209
	v_add_f32_e32 v225, v195, v225
	ds_write2_b32 v78, v208, v209 offset0:0 offset1:1
	ds_write2_b32 v79, v224, v225 offset0:0 offset1:1
	s_waitcnt lgkmcnt(14)
	v_mul_f32_e32 v194, v73, v225
	v_mul_f32_e32 v195, v73, v209
	v_fma_f32 v194, v72, v209, -v194
	v_fma_f32 v195, v72, v225, v195
	v_add_f32_e32 v210, v194, v210
	v_add_f32_e32 v226, v195, v226
	v_mul_f32_e32 v194, v73, v226
	v_mul_f32_e32 v195, v73, v210
	v_fma_f32 v194, v72, v210, -v194
	v_fma_f32 v195, v72, v226, v195
	v_add_f32_e32 v211, v194, v211
	v_add_f32_e32 v227, v195, v227
	ds_write2_b32 v78, v210, v211 offset0:2 offset1:3
	ds_write2_b32 v79, v226, v227 offset0:2 offset1:3
	s_waitcnt lgkmcnt(14)
	v_mul_f32_e32 v194, v73, v227
	v_mul_f32_e32 v195, v73, v211
	v_fma_f32 v194, v72, v211, -v194
	v_fma_f32 v195, v72, v227, v195
	v_add_f32_e32 v212, v194, v212
	v_add_f32_e32 v228, v195, v228
	v_mul_f32_e32 v194, v73, v228
	v_mul_f32_e32 v195, v73, v212
	v_fma_f32 v194, v72, v212, -v194
	v_fma_f32 v195, v72, v228, v195
	v_add_f32_e32 v213, v194, v213
	v_add_f32_e32 v229, v195, v229
	ds_write2_b32 v78, v212, v213 offset0:4 offset1:5
	ds_write2_b32 v79, v228, v229 offset0:4 offset1:5
	s_waitcnt lgkmcnt(14)
	v_mul_f32_e32 v194, v73, v229
	v_mul_f32_e32 v195, v73, v213
	v_fma_f32 v194, v72, v213, -v194
	v_fma_f32 v195, v72, v229, v195
	v_add_f32_e32 v214, v194, v214
	v_add_f32_e32 v230, v195, v230
	v_mul_f32_e32 v194, v73, v230
	v_mul_f32_e32 v195, v73, v214
	v_fma_f32 v194, v72, v214, -v194
	v_fma_f32 v195, v72, v230, v195
	v_add_f32_e32 v215, v194, v215
	v_add_f32_e32 v231, v195, v231
	ds_write2_b32 v78, v214, v215 offset0:6 offset1:7
	ds_write2_b32 v79, v230, v231 offset0:6 offset1:7
	s_waitcnt lgkmcnt(14)
	v_mul_f32_e32 v194, v73, v231
	v_mul_f32_e32 v195, v73, v215
	v_fma_f32 v194, v72, v215, -v194
	v_fma_f32 v195, v72, v231, v195
	v_add_f32_e32 v216, v194, v216
	v_add_f32_e32 v232, v195, v232
	v_mul_f32_e32 v194, v73, v232
	v_mul_f32_e32 v195, v73, v216
	v_fma_f32 v194, v72, v216, -v194
	v_fma_f32 v195, v72, v232, v195
	v_add_f32_e32 v217, v194, v217
	v_add_f32_e32 v233, v195, v233
	ds_write2_b32 v78, v216, v217 offset0:8 offset1:9
	ds_write2_b32 v79, v232, v233 offset0:8 offset1:9
	s_waitcnt lgkmcnt(14)
	v_mul_f32_e32 v194, v73, v233
	v_mul_f32_e32 v195, v73, v217
	v_fma_f32 v194, v72, v217, -v194
	v_fma_f32 v195, v72, v233, v195
	v_add_f32_e32 v218, v194, v218
	v_add_f32_e32 v234, v195, v234
	v_mul_f32_e32 v194, v73, v234
	v_mul_f32_e32 v195, v73, v218
	v_fma_f32 v194, v72, v218, -v194
	v_fma_f32 v195, v72, v234, v195
	v_add_f32_e32 v219, v194, v219
	v_add_f32_e32 v235, v195, v235
	ds_write2_b32 v78, v218, v219 offset0:10 offset1:11
	ds_write2_b32 v79, v234, v235 offset0:10 offset1:11
	s_waitcnt lgkmcnt(14)
	v_mul_f32_e32 v194, v73, v235
	v_mul_f32_e32 v195, v73, v219
	v_fma_f32 v194, v72, v219, -v194
	v_fma_f32 v195, v72, v235, v195
	v_add_f32_e32 v220, v194, v220
	v_add_f32_e32 v236, v195, v236
	v_mul_f32_e32 v194, v73, v236
	v_mul_f32_e32 v195, v73, v220
	v_fma_f32 v194, v72, v220, -v194
	v_fma_f32 v195, v72, v236, v195
	v_add_f32_e32 v221, v194, v221
	v_add_f32_e32 v237, v195, v237
	ds_write2_b32 v78, v220, v221 offset0:12 offset1:13
	ds_write2_b32 v79, v236, v237 offset0:12 offset1:13
	s_waitcnt lgkmcnt(14)
	v_mul_f32_e32 v194, v73, v237
	v_mul_f32_e32 v195, v73, v221
	v_fma_f32 v194, v72, v221, -v194
	v_fma_f32 v195, v72, v237, v195
	v_add_f32_e32 v222, v194, v222
	v_add_f32_e32 v238, v195, v238
	v_mul_f32_e32 v194, v73, v238
	v_mul_f32_e32 v195, v73, v222
	v_fma_f32 v194, v72, v222, -v194
	v_fma_f32 v195, v72, v238, v195
	v_add_f32_e32 v223, v194, v223
	v_add_f32_e32 v239, v195, v239
	ds_write2_b32 v78, v222, v223 offset0:14 offset1:15
	ds_write2_b32 v79, v238, v239 offset0:14 offset1:15
	v_mov_b32_e32 v192, v223
	v_mov_b32_e32 v193, v239
	ds_read_b32 v160, v80 offset:0
	ds_read_b32 v161, v80 offset:272
	ds_read_b32 v162, v80 offset:544
	ds_read_b32 v163, v80 offset:816
	ds_read_b32 v164, v80 offset:1088
	ds_read_b32 v165, v80 offset:1360
	ds_read_b32 v166, v80 offset:1632
	ds_read_b32 v167, v80 offset:1904
	ds_read_b32 v168, v80 offset:2176
	ds_read_b32 v169, v80 offset:2448
	ds_read_b32 v170, v80 offset:2720
	ds_read_b32 v171, v80 offset:2992
	ds_read_b32 v172, v80 offset:3264
	ds_read_b32 v173, v80 offset:3536
	ds_read_b32 v174, v80 offset:3808
	ds_read_b32 v175, v80 offset:4080
	ds_read_b32 v176, v80 offset:4352
	ds_read_b32 v177, v80 offset:4624
	ds_read_b32 v178, v80 offset:4896
	ds_read_b32 v179, v80 offset:5168
	ds_read_b32 v180, v80 offset:5440
	ds_read_b32 v181, v80 offset:5712
	ds_read_b32 v182, v80 offset:5984
	ds_read_b32 v183, v80 offset:6256
	ds_read_b32 v184, v80 offset:6528
	ds_read_b32 v185, v80 offset:6800
	ds_read_b32 v186, v80 offset:7072
	ds_read_b32 v187, v80 offset:7344
	ds_read_b32 v188, v80 offset:7616
	ds_read_b32 v189, v80 offset:7888
	ds_read_b32 v190, v80 offset:8160
	ds_read_b32 v191, v80 offset:8432
	s_waitcnt lgkmcnt(15)
	v_mfma_f32_16x16x4_f32 v[200:203], v160, v40, 0
	s_waitcnt lgkmcnt(15)
	v_mfma_f32_16x16x4_f32 v[240:243], v161, v41, 0
	s_waitcnt lgkmcnt(15)
	v_mfma_f32_16x16x4_f32 v[200:203], v162, v42, v[200:203]
	s_waitcnt lgkmcnt(15)
	v_mfma_f32_16x16x4_f32 v[240:243], v163, v43, v[240:243]
	s_waitcnt lgkmcnt(15)
	v_mfma_f32_16x16x4_f32 v[200:203], v164, v44, v[200:203]
	s_waitcnt lgkmcnt(15)
; DI unsigned pk2(float a, float b) { f32x2_t v = {a, b}; return __builtin_bit_cast(unsigned, __builtin_convertvector(v, bf16x2_t)); }
; DI float bf2f(unsigned x) { return __uint_as_float(x << 16); }
; DI float gelu_tanh(float v) { const float z = 0.7978845608028654f * (v + 0.044715f * v * v * v); const float th = 1.0f - 2.0f * __builtin_amdgcn_rcpf(__builtin_amdgcn_exp2f(2.8853900817779268f * z) + 1.0f); return 0.5f * v * (1.0f + th); }
; DI void s5_pass3_item(const Params& P, int bitem, unsigned char* smem) {
;     ...
;     for (int sub = 0; sub < 4; ++sub) {
;         s5_bu16(ubs[sub], af, xs, r, q);
;         float uv[4];
; #pragma unroll
;         for (int j = 0; j < 4; ++j) uv[j] = bf2f(uvs[sub][j]);
;         asm volatile("s_waitcnt lgkmcnt(0)" ::: "memory");
; #pragma unroll
;         for (int tt = 0; tt < 16; ++tt) { const float bur = xs[lane * 17 + tt], bui = xs[(64 + lane) * 17 + tt];
;             const float nxr = ab[0] * xr - ab[1] * xi + bur, nxi = ab[0] * xi + ab[1] * xr + bui; xr = nxr; xi = nxi;
;             xs[lane * 17 + tt] = xr; xs[(64 + lane) * 17 + tt] = xi; }
;         asm volatile("s_waitcnt lgkmcnt(0)" ::: "memory");
;         f32x4 ya[4];
; #pragma unroll
;         for (int j = 0; j < 4; ++j) ya[j] = (f32x4){0.f, 0.f, 0.f, 0.f};
; #pragma unroll
;         for (int i = 0; i < 32; ++i) { const float a = xs[(4 * i + q) * 17 + r]; ya[i & 3] = __builtin_amdgcn_mfma_f32_16x16x4f32(a, cB[i], ya[i & 3], 0, 0, 0); }
;         const f32x4 y = (ya[0] + ya[1]) + (ya[2] + ya[3]);
; #pragma unroll
;         for (int j = 0; j < 4; ++j) { const int tl = sub * 16 + 4 * q + j; const float v = y[j] + dsk * uv[j];
;             HG[(size_t)(b * TT + ch * 64 + tl) * 1024 + grp * 16 + r] = (bf16_t)(pk2(gelu_tanh(v), 0.f) & 0xffffu); }
	v_mfma_f32_16x16x4_f32 v[240:243], v165, v45, v[240:243]
	s_waitcnt lgkmcnt(15)
	v_mfma_f32_16x16x4_f32 v[200:203], v166, v46, v[200:203]
	s_waitcnt lgkmcnt(15)
	v_mfma_f32_16x16x4_f32 v[240:243], v167, v47, v[240:243]
	s_waitcnt lgkmcnt(15)
	v_mfma_f32_16x16x4_f32 v[200:203], v168, v48, v[200:203]
	s_waitcnt lgkmcnt(15)
	v_mfma_f32_16x16x4_f32 v[240:243], v169, v49, v[240:243]
	s_waitcnt lgkmcnt(15)
	v_mfma_f32_16x16x4_f32 v[200:203], v170, v50, v[200:203]
	s_waitcnt lgkmcnt(15)
	v_mfma_f32_16x16x4_f32 v[240:243], v171, v51, v[240:243]
	s_waitcnt lgkmcnt(15)
	v_mfma_f32_16x16x4_f32 v[200:203], v172, v52, v[200:203]
	s_waitcnt lgkmcnt(15)
	v_mfma_f32_16x16x4_f32 v[240:243], v173, v53, v[240:243]
	s_waitcnt lgkmcnt(15)
	v_mfma_f32_16x16x4_f32 v[200:203], v174, v54, v[200:203]
	s_waitcnt lgkmcnt(15)
	v_mfma_f32_16x16x4_f32 v[240:243], v175, v55, v[240:243]
	s_waitcnt lgkmcnt(15)
	v_mfma_f32_16x16x4_f32 v[200:203], v176, v56, v[200:203]
	s_waitcnt lgkmcnt(14)
	v_mfma_f32_16x16x4_f32 v[240:243], v177, v57, v[240:243]
	s_waitcnt lgkmcnt(13)
	v_mfma_f32_16x16x4_f32 v[200:203], v178, v58, v[200:203]
	s_waitcnt lgkmcnt(12)
	v_mfma_f32_16x16x4_f32 v[240:243], v179, v59, v[240:243]
	s_waitcnt lgkmcnt(11)
	v_mfma_f32_16x16x4_f32 v[200:203], v180, v60, v[200:203]
	s_waitcnt lgkmcnt(10)
	v_mfma_f32_16x16x4_f32 v[240:243], v181, v61, v[240:243]
	s_waitcnt lgkmcnt(9)
	v_mfma_f32_16x16x4_f32 v[200:203], v182, v62, v[200:203]
	s_waitcnt lgkmcnt(8)
	v_mfma_f32_16x16x4_f32 v[240:243], v183, v63, v[240:243]
	s_waitcnt lgkmcnt(7)
	v_mfma_f32_16x16x4_f32 v[200:203], v184, v64, v[200:203]
	s_waitcnt lgkmcnt(6)
	v_mfma_f32_16x16x4_f32 v[240:243], v185, v65, v[240:243]
	s_waitcnt lgkmcnt(5)
	v_mfma_f32_16x16x4_f32 v[200:203], v186, v66, v[200:203]
	s_waitcnt lgkmcnt(4)
	v_mfma_f32_16x16x4_f32 v[240:243], v187, v67, v[240:243]
	s_waitcnt lgkmcnt(3)
	v_mfma_f32_16x16x4_f32 v[200:203], v188, v68, v[200:203]
	s_waitcnt lgkmcnt(2)
	v_mfma_f32_16x16x4_f32 v[240:243], v189, v69, v[240:243]
	s_waitcnt lgkmcnt(1)
	v_mfma_f32_16x16x4_f32 v[200:203], v190, v70, v[200:203]
	s_waitcnt lgkmcnt(0)
	v_mfma_f32_16x16x4_f32 v[240:243], v191, v71, v[240:243]
	s_nop 9
	v_add_f32_e32 v1, v200, v240
	v_add_f32_e32 v2, v201, v241
	v_add_f32_e32 v3, v202, v242
	v_add_f32_e32 v4, v203, v243
	v_fmac_f32_e32 v1, v76, v112
	v_fmac_f32_e32 v2, v76, v113
	v_fmac_f32_e32 v3, v76, v114
	v_fmac_f32_e32 v4, v76, v115
	v_mul_f32_e32 v5, 0x3d372713, v1
	v_mul_f32_e32 v6, 0x3d372713, v2
	v_mul_f32_e32 v7, 0x3d372713, v3
	v_mul_f32_e32 v246, 0x3d372713, v4
	v_mul_f32_e32 v5, v1, v5
	v_mul_f32_e32 v6, v2, v6
	v_mul_f32_e32 v7, v3, v7
	v_mul_f32_e32 v246, v4, v246
	v_mul_f32_e32 v194, 0.5, v1
	v_mul_f32_e32 v195, 0.5, v2
	v_mul_f32_e32 v196, 0.5, v3
	v_mul_f32_e32 v197, 0.5, v4
	v_fma_f32 v1, v1, v5, v1
	v_fma_f32 v2, v2, v6, v2
	v_fma_f32 v3, v3, v7, v3
	v_fma_f32 v4, v4, v246, v4
	v_mul_f32_e32 v1, 0x3f4c422a, v1
	v_mul_f32_e32 v2, 0x3f4c422a, v2
	v_mul_f32_e32 v3, 0x3f4c422a, v3
	v_mul_f32_e32 v4, 0x3f4c422a, v4
	v_mul_f32_e32 v1, 0x4038aa3b, v1
	v_mul_f32_e32 v2, 0x4038aa3b, v2
	v_mul_f32_e32 v3, 0x4038aa3b, v3
	v_mul_f32_e32 v4, 0x4038aa3b, v4
	v_exp_f32_e32 v1, v1
	v_exp_f32_e32 v2, v2
	v_exp_f32_e32 v3, v3
	v_exp_f32_e32 v4, v4
	v_add_f32_e32 v1, 1.0, v1
	v_add_f32_e32 v2, 1.0, v2
	v_add_f32_e32 v3, 1.0, v3
	v_add_f32_e32 v4, 1.0, v4
	v_rcp_f32_e32 v1, v1
	v_rcp_f32_e32 v2, v2
	v_rcp_f32_e32 v3, v3
	v_rcp_f32_e32 v4, v4
	v_fma_f32 v1, v1, -2.0, 1.0
	v_fma_f32 v2, v2, -2.0, 1.0
	v_fma_f32 v3, v3, -2.0, 1.0
	v_fma_f32 v4, v4, -2.0, 1.0
	v_add_f32_e32 v1, 1.0, v1
	v_add_f32_e32 v2, 1.0, v2
	v_add_f32_e32 v3, 1.0, v3
	v_add_f32_e32 v4, 1.0, v4
	v_mul_f32_e32 v1, v194, v1
	v_mul_f32_e32 v2, v195, v2
	v_mul_f32_e32 v3, v196, v3
	v_mul_f32_e32 v4, v197, v4
	v_cvt_pk_bf16_f32 v1, v1, v1
	v_cvt_pk_bf16_f32 v2, v2, v2
	v_cvt_pk_bf16_f32 v3, v3, v3
	v_cvt_pk_bf16_f32 v4, v4, v4
	global_store_short v198, v1, s[28:29] offset:-4096
	global_store_short v198, v2, s[28:29] offset:-2048
	global_store_short v198, v3, s[28:29] offset:0
	global_store_short v198, v4, s[28:29] offset:2048
	s_add_u32 s28, s28, 0x8000
	s_addc_u32 s29, s29, 0
	v_mfma_f32_16x16x32_bf16 v[160:163], v[8:11], v[100:103], 0
	v_mfma_f32_16x16x32_bf16 v[164:167], v[12:15], v[100:103], 0
	v_mfma_f32_16x16x32_bf16 v[168:171], v[16:19], v[100:103], 0
	v_mfma_f32_16x16x32_bf16 v[172:175], v[20:23], v[100:103], 0
	v_mfma_f32_16x16x32_bf16 v[176:179], v[24:27], v[100:103], 0
	v_mfma_f32_16x16x32_bf16 v[180:183], v[28:31], v[100:103], 0
	v_mfma_f32_16x16x32_bf16 v[184:187], v[32:35], v[100:103], 0
	v_mfma_f32_16x16x32_bf16 v[188:191], v[36:39], v[100:103], 0
	s_nop 1
	ds_write_b32 v77, v160 offset:0
	ds_write_b32 v77, v161 offset:68
	ds_write_b32 v77, v162 offset:136
	ds_write_b32 v77, v163 offset:204
	ds_write_b32 v77, v164 offset:1088
	ds_write_b32 v77, v165 offset:1156
	ds_write_b32 v77, v166 offset:1224
	ds_write_b32 v77, v167 offset:1292
	ds_write_b32 v77, v168 offset:2176
	ds_write_b32 v77, v169 offset:2244
	ds_write_b32 v77, v170 offset:2312
	ds_write_b32 v77, v171 offset:2380
	ds_write_b32 v77, v172 offset:3264
	ds_write_b32 v77, v173 offset:3332
	ds_write_b32 v77, v174 offset:3400
	ds_write_b32 v77, v175 offset:3468
	ds_write_b32 v77, v176 offset:4352
	ds_write_b32 v77, v177 offset:4420
	ds_write_b32 v77, v178 offset:4488
	ds_write_b32 v77, v179 offset:4556
	ds_write_b32 v77, v180 offset:5440
	ds_write_b32 v77, v181 offset:5508
	ds_write_b32 v77, v182 offset:5576
	ds_write_b32 v77, v183 offset:5644
	ds_write_b32 v77, v184 offset:6528
	ds_write_b32 v77, v185 offset:6596
	ds_write_b32 v77, v186 offset:6664
	ds_write_b32 v77, v187 offset:6732
	ds_write_b32 v77, v188 offset:7616
	ds_write_b32 v77, v189 offset:7684
	ds_write_b32 v77, v190 offset:7752
	ds_write_b32 v77, v191 offset:7820
	ds_read2_b32 v[208:209], v78 offset0:0 offset1:1
	ds_read2_b32 v[224:225], v79 offset0:0 offset1:1
	ds_read2_b32 v[210:211], v78 offset0:2 offset1:3
	ds_read2_b32 v[226:227], v79 offset0:2 offset1:3
	ds_read2_b32 v[212:213], v78 offset0:4 offset1:5
	ds_read2_b32 v[228:229], v79 offset0:4 offset1:5
	ds_read2_b32 v[214:215], v78 offset0:6 offset1:7
	ds_read2_b32 v[230:231], v79 offset0:6 offset1:7
	ds_read2_b32 v[216:217], v78 offset0:8 offset1:9
	ds_read2_b32 v[232:233], v79 offset0:8 offset1:9
	ds_read2_b32 v[218:219], v78 offset0:10 offset1:11
	ds_read2_b32 v[234:235], v79 offset0:10 offset1:11
	ds_read2_b32 v[220:221], v78 offset0:12 offset1:13
	ds_read2_b32 v[236:237], v79 offset0:12 offset1:13
	ds_read2_b32 v[222:223], v78 offset0:14 offset1:15
	ds_read2_b32 v[238:239], v79 offset0:14 offset1:15
	s_waitcnt lgkmcnt(14)
; DI void s5_pass3_item(const Params& P, int bitem, unsigned char* smem) {
;     ...
; #pragma unroll
;         for (int tt = 0; tt < 16; ++tt) { const float bur = xs[lane * 17 + tt], bui = xs[(64 + lane) * 17 + tt];
;             const float nxr = ab[0] * xr - ab[1] * xi + bur, nxi = ab[0] * xi + ab[1] * xr + bui; xr = nxr; xi = nxi;
;             xs[lane * 17 + tt] = xr; xs[(64 + lane) * 17 + tt] = xi; }
;         asm volatile("s_waitcnt lgkmcnt(0)" ::: "memory");
;         f32x4 ya[4];
; #pragma unroll
;         for (int j = 0; j < 4; ++j) ya[j] = (f32x4){0.f, 0.f, 0.f, 0.f};
; #pragma unroll
;         for (int i = 0; i < 32; ++i) { const float a = xs[(4 * i + q) * 17 + r]; ya[i & 3] = __builtin_amdgcn_mfma_f32_16x16x4f32(a, cB[i], ya[i & 3], 0, 0, 0); }
;         const f32x4 y = (ya[0] + ya[1]) + (ya[2] + ya[3]);
	v_mul_f32_e32 v194, v73, v193
	v_mul_f32_e32 v195, v73, v192
	v_fma_f32 v194, v72, v192, -v194
	v_fma_f32 v195, v72, v193, v195
	v_add_f32_e32 v208, v194, v208
	v_add_f32_e32 v224, v195, v224
	v_mul_f32_e32 v194, v73, v224
	v_mul_f32_e32 v195, v73, v208
	v_fma_f32 v194, v72, v208, -v194
	v_fma_f32 v195, v72, v224, v195
	v_add_f32_e32 v209, v194, v209
	v_add_f32_e32 v225, v195, v225
	ds_write2_b32 v78, v208, v209 offset0:0 offset1:1
	ds_write2_b32 v79, v224, v225 offset0:0 offset1:1
	s_waitcnt lgkmcnt(14)
	v_mul_f32_e32 v194, v73, v225
	v_mul_f32_e32 v195, v73, v209
	v_fma_f32 v194, v72, v209, -v194
	v_fma_f32 v195, v72, v225, v195
	v_add_f32_e32 v210, v194, v210
	v_add_f32_e32 v226, v195, v226
	v_mul_f32_e32 v194, v73, v226
	v_mul_f32_e32 v195, v73, v210
	v_fma_f32 v194, v72, v210, -v194
	v_fma_f32 v195, v72, v226, v195
	v_add_f32_e32 v211, v194, v211
	v_add_f32_e32 v227, v195, v227
	ds_write2_b32 v78, v210, v211 offset0:2 offset1:3
	ds_write2_b32 v79, v226, v227 offset0:2 offset1:3
	s_waitcnt lgkmcnt(14)
	v_mul_f32_e32 v194, v73, v227
	v_mul_f32_e32 v195, v73, v211
	v_fma_f32 v194, v72, v211, -v194
	v_fma_f32 v195, v72, v227, v195
	v_add_f32_e32 v212, v194, v212
	v_add_f32_e32 v228, v195, v228
	v_mul_f32_e32 v194, v73, v228
	v_mul_f32_e32 v195, v73, v212
	v_fma_f32 v194, v72, v212, -v194
	v_fma_f32 v195, v72, v228, v195
	v_add_f32_e32 v213, v194, v213
	v_add_f32_e32 v229, v195, v229
	ds_write2_b32 v78, v212, v213 offset0:4 offset1:5
	ds_write2_b32 v79, v228, v229 offset0:4 offset1:5
	s_waitcnt lgkmcnt(14)
	v_mul_f32_e32 v194, v73, v229
	v_mul_f32_e32 v195, v73, v213
	v_fma_f32 v194, v72, v213, -v194
	v_fma_f32 v195, v72, v229, v195
	v_add_f32_e32 v214, v194, v214
	v_add_f32_e32 v230, v195, v230
	v_mul_f32_e32 v194, v73, v230
	v_mul_f32_e32 v195, v73, v214
	v_fma_f32 v194, v72, v214, -v194
	v_fma_f32 v195, v72, v230, v195
	v_add_f32_e32 v215, v194, v215
	v_add_f32_e32 v231, v195, v231
	ds_write2_b32 v78, v214, v215 offset0:6 offset1:7
	ds_write2_b32 v79, v230, v231 offset0:6 offset1:7
	s_waitcnt lgkmcnt(14)
	v_mul_f32_e32 v194, v73, v231
	v_mul_f32_e32 v195, v73, v215
	v_fma_f32 v194, v72, v215, -v194
	v_fma_f32 v195, v72, v231, v195
	v_add_f32_e32 v216, v194, v216
	v_add_f32_e32 v232, v195, v232
	v_mul_f32_e32 v194, v73, v232
	v_mul_f32_e32 v195, v73, v216
	v_fma_f32 v194, v72, v216, -v194
	v_fma_f32 v195, v72, v232, v195
	v_add_f32_e32 v217, v194, v217
	v_add_f32_e32 v233, v195, v233
	ds_write2_b32 v78, v216, v217 offset0:8 offset1:9
	ds_write2_b32 v79, v232, v233 offset0:8 offset1:9
	s_waitcnt lgkmcnt(14)
	v_mul_f32_e32 v194, v73, v233
	v_mul_f32_e32 v195, v73, v217
	v_fma_f32 v194, v72, v217, -v194
	v_fma_f32 v195, v72, v233, v195
	v_add_f32_e32 v218, v194, v218
	v_add_f32_e32 v234, v195, v234
	v_mul_f32_e32 v194, v73, v234
	v_mul_f32_e32 v195, v73, v218
	v_fma_f32 v194, v72, v218, -v194
	v_fma_f32 v195, v72, v234, v195
	v_add_f32_e32 v219, v194, v219
	v_add_f32_e32 v235, v195, v235
	ds_write2_b32 v78, v218, v219 offset0:10 offset1:11
	ds_write2_b32 v79, v234, v235 offset0:10 offset1:11
	s_waitcnt lgkmcnt(14)
	v_mul_f32_e32 v194, v73, v235
	v_mul_f32_e32 v195, v73, v219
	v_fma_f32 v194, v72, v219, -v194
	v_fma_f32 v195, v72, v235, v195
	v_add_f32_e32 v220, v194, v220
	v_add_f32_e32 v236, v195, v236
	v_mul_f32_e32 v194, v73, v236
	v_mul_f32_e32 v195, v73, v220
	v_fma_f32 v194, v72, v220, -v194
	v_fma_f32 v195, v72, v236, v195
	v_add_f32_e32 v221, v194, v221
	v_add_f32_e32 v237, v195, v237
	ds_write2_b32 v78, v220, v221 offset0:12 offset1:13
	ds_write2_b32 v79, v236, v237 offset0:12 offset1:13
	s_waitcnt lgkmcnt(14)
	v_mul_f32_e32 v194, v73, v237
	v_mul_f32_e32 v195, v73, v221
	v_fma_f32 v194, v72, v221, -v194
	v_fma_f32 v195, v72, v237, v195
	v_add_f32_e32 v222, v194, v222
	v_add_f32_e32 v238, v195, v238
	v_mul_f32_e32 v194, v73, v238
	v_mul_f32_e32 v195, v73, v222
	v_fma_f32 v194, v72, v222, -v194
	v_fma_f32 v195, v72, v238, v195
	v_add_f32_e32 v223, v194, v223
	v_add_f32_e32 v239, v195, v239
	ds_write2_b32 v78, v222, v223 offset0:14 offset1:15
	ds_write2_b32 v79, v238, v239 offset0:14 offset1:15
	v_mov_b32_e32 v192, v223
	v_mov_b32_e32 v193, v239
	ds_read_b32 v160, v80 offset:0
	ds_read_b32 v161, v80 offset:272
	ds_read_b32 v162, v80 offset:544
	ds_read_b32 v163, v80 offset:816
	ds_read_b32 v164, v80 offset:1088
	ds_read_b32 v165, v80 offset:1360
	ds_read_b32 v166, v80 offset:1632
	ds_read_b32 v167, v80 offset:1904
	ds_read_b32 v168, v80 offset:2176
	ds_read_b32 v169, v80 offset:2448
	ds_read_b32 v170, v80 offset:2720
	ds_read_b32 v171, v80 offset:2992
	ds_read_b32 v172, v80 offset:3264
	ds_read_b32 v173, v80 offset:3536
	ds_read_b32 v174, v80 offset:3808
	ds_read_b32 v175, v80 offset:4080
	ds_read_b32 v176, v80 offset:4352
	ds_read_b32 v177, v80 offset:4624
	ds_read_b32 v178, v80 offset:4896
	ds_read_b32 v179, v80 offset:5168
	ds_read_b32 v180, v80 offset:5440
	ds_read_b32 v181, v80 offset:5712
	ds_read_b32 v182, v80 offset:5984
	ds_read_b32 v183, v80 offset:6256
	ds_read_b32 v184, v80 offset:6528
	ds_read_b32 v185, v80 offset:6800
	ds_read_b32 v186, v80 offset:7072
	ds_read_b32 v187, v80 offset:7344
	ds_read_b32 v188, v80 offset:7616
	ds_read_b32 v189, v80 offset:7888
	ds_read_b32 v190, v80 offset:8160
	ds_read_b32 v191, v80 offset:8432
	s_waitcnt lgkmcnt(15)
; DI unsigned pk2(float a, float b) { f32x2_t v = {a, b}; return __builtin_bit_cast(unsigned, __builtin_convertvector(v, bf16x2_t)); }
; DI float gelu_tanh(float v) { const float z = 0.7978845608028654f * (v + 0.044715f * v * v * v); const float th = 1.0f - 2.0f * __builtin_amdgcn_rcpf(__builtin_amdgcn_exp2f(2.8853900817779268f * z) + 1.0f); return 0.5f * v * (1.0f + th); }
; DI void s5_pass3_item(const Params& P, int bitem, unsigned char* smem) {
;     ...
;         f32x4 ya[4];
; #pragma unroll
;         for (int j = 0; j < 4; ++j) ya[j] = (f32x4){0.f, 0.f, 0.f, 0.f};
; #pragma unroll
;         for (int i = 0; i < 32; ++i) { const float a = xs[(4 * i + q) * 17 + r]; ya[i & 3] = __builtin_amdgcn_mfma_f32_16x16x4f32(a, cB[i], ya[i & 3], 0, 0, 0); }
;         const f32x4 y = (ya[0] + ya[1]) + (ya[2] + ya[3]);
; #pragma unroll
;         for (int j = 0; j < 4; ++j) { const int tl = sub * 16 + 4 * q + j; const float v = y[j] + dsk * uv[j];
;             HG[(size_t)(b * TT + ch * 64 + tl) * 1024 + grp * 16 + r] = (bf16_t)(pk2(gelu_tanh(v), 0.f) & 0xffffu); }
;         asm volatile("s_waitcnt lgkmcnt(0)" ::: "memory");
;     }
	v_mfma_f32_16x16x4_f32 v[200:203], v160, v40, 0
	s_waitcnt lgkmcnt(15)
	v_mfma_f32_16x16x4_f32 v[240:243], v161, v41, 0
	s_waitcnt lgkmcnt(15)
	v_mfma_f32_16x16x4_f32 v[200:203], v162, v42, v[200:203]
	s_waitcnt lgkmcnt(15)
	v_mfma_f32_16x16x4_f32 v[240:243], v163, v43, v[240:243]
	s_waitcnt lgkmcnt(15)
	v_mfma_f32_16x16x4_f32 v[200:203], v164, v44, v[200:203]
	s_waitcnt lgkmcnt(15)
	v_mfma_f32_16x16x4_f32 v[240:243], v165, v45, v[240:243]
	s_waitcnt lgkmcnt(15)
	v_mfma_f32_16x16x4_f32 v[200:203], v166, v46, v[200:203]
	s_waitcnt lgkmcnt(15)
	v_mfma_f32_16x16x4_f32 v[240:243], v167, v47, v[240:243]
	s_waitcnt lgkmcnt(15)
	v_mfma_f32_16x16x4_f32 v[200:203], v168, v48, v[200:203]
	s_waitcnt lgkmcnt(15)
	v_mfma_f32_16x16x4_f32 v[240:243], v169, v49, v[240:243]
	s_waitcnt lgkmcnt(15)
	v_mfma_f32_16x16x4_f32 v[200:203], v170, v50, v[200:203]
	s_waitcnt lgkmcnt(15)
	v_mfma_f32_16x16x4_f32 v[240:243], v171, v51, v[240:243]
	s_waitcnt lgkmcnt(15)
	v_mfma_f32_16x16x4_f32 v[200:203], v172, v52, v[200:203]
	s_waitcnt lgkmcnt(15)
	v_mfma_f32_16x16x4_f32 v[240:243], v173, v53, v[240:243]
	s_waitcnt lgkmcnt(15)
	v_mfma_f32_16x16x4_f32 v[200:203], v174, v54, v[200:203]
	s_waitcnt lgkmcnt(15)
	v_mfma_f32_16x16x4_f32 v[240:243], v175, v55, v[240:243]
	s_waitcnt lgkmcnt(15)
	v_mfma_f32_16x16x4_f32 v[200:203], v176, v56, v[200:203]
	s_waitcnt lgkmcnt(14)
	v_mfma_f32_16x16x4_f32 v[240:243], v177, v57, v[240:243]
	s_waitcnt lgkmcnt(13)
	v_mfma_f32_16x16x4_f32 v[200:203], v178, v58, v[200:203]
	s_waitcnt lgkmcnt(12)
	v_mfma_f32_16x16x4_f32 v[240:243], v179, v59, v[240:243]
	s_waitcnt lgkmcnt(11)
	v_mfma_f32_16x16x4_f32 v[200:203], v180, v60, v[200:203]
	s_waitcnt lgkmcnt(10)
	v_mfma_f32_16x16x4_f32 v[240:243], v181, v61, v[240:243]
	s_waitcnt lgkmcnt(9)
	v_mfma_f32_16x16x4_f32 v[200:203], v182, v62, v[200:203]
	s_waitcnt lgkmcnt(8)
	v_mfma_f32_16x16x4_f32 v[240:243], v183, v63, v[240:243]
	s_waitcnt lgkmcnt(7)
	v_mfma_f32_16x16x4_f32 v[200:203], v184, v64, v[200:203]
	s_waitcnt lgkmcnt(6)
	v_mfma_f32_16x16x4_f32 v[240:243], v185, v65, v[240:243]
	s_waitcnt lgkmcnt(5)
	v_mfma_f32_16x16x4_f32 v[200:203], v186, v66, v[200:203]
	s_waitcnt lgkmcnt(4)
	v_mfma_f32_16x16x4_f32 v[240:243], v187, v67, v[240:243]
	s_waitcnt lgkmcnt(3)
	v_mfma_f32_16x16x4_f32 v[200:203], v188, v68, v[200:203]
	s_waitcnt lgkmcnt(2)
	v_mfma_f32_16x16x4_f32 v[240:243], v189, v69, v[240:243]
	s_waitcnt lgkmcnt(1)
	v_mfma_f32_16x16x4_f32 v[200:203], v190, v70, v[200:203]
	s_waitcnt lgkmcnt(0)
	v_mfma_f32_16x16x4_f32 v[240:243], v191, v71, v[240:243]
	s_nop 9
	v_add_f32_e32 v1, v200, v240
	v_add_f32_e32 v2, v201, v241
	v_add_f32_e32 v3, v202, v242
	v_add_f32_e32 v4, v203, v243
	v_fmac_f32_e32 v1, v76, v116
	v_fmac_f32_e32 v2, v76, v117
	v_fmac_f32_e32 v3, v76, v118
	v_fmac_f32_e32 v4, v76, v119
	v_mul_f32_e32 v5, 0x3d372713, v1
	v_mul_f32_e32 v6, 0x3d372713, v2
	v_mul_f32_e32 v7, 0x3d372713, v3
	v_mul_f32_e32 v246, 0x3d372713, v4
	v_mul_f32_e32 v5, v1, v5
	v_mul_f32_e32 v6, v2, v6
	v_mul_f32_e32 v7, v3, v7
	v_mul_f32_e32 v246, v4, v246
	v_mul_f32_e32 v194, 0.5, v1
	v_mul_f32_e32 v195, 0.5, v2
	v_mul_f32_e32 v196, 0.5, v3
	v_mul_f32_e32 v197, 0.5, v4
	v_fma_f32 v1, v1, v5, v1
	v_fma_f32 v2, v2, v6, v2
	v_fma_f32 v3, v3, v7, v3
	v_fma_f32 v4, v4, v246, v4
	v_mul_f32_e32 v1, 0x3f4c422a, v1
	v_mul_f32_e32 v2, 0x3f4c422a, v2
	v_mul_f32_e32 v3, 0x3f4c422a, v3
	v_mul_f32_e32 v4, 0x3f4c422a, v4
	v_mul_f32_e32 v1, 0x4038aa3b, v1
	v_mul_f32_e32 v2, 0x4038aa3b, v2
	v_mul_f32_e32 v3, 0x4038aa3b, v3
	v_mul_f32_e32 v4, 0x4038aa3b, v4
	v_exp_f32_e32 v1, v1
	v_exp_f32_e32 v2, v2
	v_exp_f32_e32 v3, v3
	v_exp_f32_e32 v4, v4
	v_add_f32_e32 v1, 1.0, v1
	v_add_f32_e32 v2, 1.0, v2
	v_add_f32_e32 v3, 1.0, v3
	v_add_f32_e32 v4, 1.0, v4
	v_rcp_f32_e32 v1, v1
	v_rcp_f32_e32 v2, v2
	v_rcp_f32_e32 v3, v3
	v_rcp_f32_e32 v4, v4
	v_fma_f32 v1, v1, -2.0, 1.0
	v_fma_f32 v2, v2, -2.0, 1.0
	v_fma_f32 v3, v3, -2.0, 1.0
	v_fma_f32 v4, v4, -2.0, 1.0
	v_add_f32_e32 v1, 1.0, v1
	v_add_f32_e32 v2, 1.0, v2
	v_add_f32_e32 v3, 1.0, v3
	v_add_f32_e32 v4, 1.0, v4
	v_mul_f32_e32 v1, v194, v1
	v_mul_f32_e32 v2, v195, v2
	v_mul_f32_e32 v3, v196, v3
	v_mul_f32_e32 v4, v197, v4
	v_cvt_pk_bf16_f32 v1, v1, v1
	v_cvt_pk_bf16_f32 v2, v2, v2
	v_cvt_pk_bf16_f32 v3, v3, v3
	v_cvt_pk_bf16_f32 v4, v4, v4
	global_store_short v198, v1, s[28:29] offset:-4096
	global_store_short v198, v2, s[28:29] offset:-2048
	global_store_short v198, v3, s[28:29] offset:0
	global_store_short v198, v4, s[28:29] offset:2048
	s_add_u32 s26, s26, 0x400000
	s_addc_u32 s27, s27, 0
	s_xor_b32 s20, s20, 0x4000
	s_add_i32 s19, s19, 1
	s_cmp_lt_u32 s19, 8
	s_cbranch_scc1 .Ls5n_round
	s_waitcnt vmcnt(0) lgkmcnt(0)
	s_barrier
	s_branch .LBB0_727
